# padded in-proj tiles: also skip the LDS fragment reads of the skipped column half
# baseline (speedup 1.0000x reference)
.LBB0_345:
	s_add_i32 s60, s24, 2
	s_add_u32 s26, s22, 0x80
	s_addc_u32 s25, s23, 0
	s_add_i32 s61, 0, 0x10000
	v_add_u32_e32 v178, s61, v175
	ds_read_b128 v[130:133], v178
	ds_read_b128 v[134:137], v178 offset:1024
	ds_read_b128 v[156:159], v178 offset:2048
	ds_read_b128 v[178:181], v178 offset:3072
	s_cmp_eq_u32 s42, s24
	s_cselect_b32 s24, s8, s26
	s_cselect_b32 s25, s9, s25
	s_cselect_b32 s27, s11, s59
	s_cselect_b32 s26, s10, s55
	v_lshl_add_u64 v[202:203], s[22:23], 0, v[152:153]
	s_add_i32 m0, s35, 0xc000
	ds_read_b128 v[182:185], v177
	ds_read_b128 v[186:189], v177 offset:1024
	ds_read_b128 v[190:193], v177 offset:2048
	ds_read_b128 v[194:197], v177 offset:3072
	ds_read_b128 v[198:201], v177 offset:4096
	ds_read_b128 v[206:209], v177 offset:5120
	ds_read_b128 v[210:213], v177 offset:6144
	ds_read_b128 v[214:217], v177 offset:7168
	global_load_lds_dwordx4 v[202:203], off
	v_lshl_add_u64 v[202:203], s[22:23], 0, v[154:155]
	s_add_i32 m0, s35, 0xe000
	s_nop 0
	global_load_lds_dwordx4 v[202:203], off
	s_waitcnt lgkmcnt(8)
	s_barrier
	s_waitcnt lgkmcnt(0)
	s_setprio 1
	s_waitcnt lgkmcnt(0)
	v_mfma_f32_16x16x32_bf16 v[126:129], v[130:133], v[182:185], v[126:129]
	v_mfma_f32_16x16x32_bf16 v[122:125], v[156:159], v[182:185], v[122:125]
	v_mfma_f32_16x16x32_bf16 v[110:113], v[130:133], v[190:193], v[110:113]
	v_mfma_f32_16x16x32_bf16 v[106:109], v[156:159], v[190:193], v[106:109]
	v_mfma_f32_16x16x32_bf16 v[94:97], v[130:133], v[198:201], v[94:97]
	v_mfma_f32_16x16x32_bf16 v[90:93], v[156:159], v[198:201], v[90:93]
	v_mfma_f32_16x16x32_bf16 v[78:81], v[130:133], v[210:213], v[78:81]
	v_mfma_f32_16x16x32_bf16 v[74:77], v[156:159], v[210:213], v[74:77]
	v_mfma_f32_16x16x32_bf16 v[126:129], v[134:137], v[186:189], v[126:129]
	v_mfma_f32_16x16x32_bf16 v[122:125], v[178:181], v[186:189], v[122:125]
	v_mfma_f32_16x16x32_bf16 v[110:113], v[134:137], v[194:197], v[110:113]
	v_mfma_f32_16x16x32_bf16 v[106:109], v[178:181], v[194:197], v[106:109]
	v_mfma_f32_16x16x32_bf16 v[94:97], v[134:137], v[206:209], v[94:97]
	v_mfma_f32_16x16x32_bf16 v[90:93], v[178:181], v[206:209], v[90:93]
	v_mfma_f32_16x16x32_bf16 v[78:81], v[134:137], v[214:217], v[78:81]
	v_mfma_f32_16x16x32_bf16 v[74:77], v[178:181], v[214:217], v[74:77]
	s_setprio 0
	s_barrier
	s_add_i32 s64, 0, 0x14000
	v_add_u32_e32 v202, s64, v175
	s_add_i32 s61, s61, s34
	s_cmp_eq_u32 s53, 16
	s_cbranch_scc1 .Lgm_ry1
	ds_read_b128 v[218:221], v202
	ds_read_b128 v[222:225], v202 offset:1024
	ds_read_b128 v[226:229], v202 offset:2048
	ds_read_b128 v[230:233], v202 offset:3072
.Lgm_ry1:
	v_lshl_add_u64 v[202:203], s[26:27], 0, v[0:1]
	s_mov_b32 m0, s61
	v_lshl_add_u64 v[234:235], s[26:27], 0, v[150:151]
	global_load_lds_dwordx4 v[202:203], off
	s_add_i32 m0, s61, 0x2000
	s_nop 0
	global_load_lds_dwordx4 v[234:235], off
	s_barrier
	s_waitcnt lgkmcnt(0)
	s_setprio 1
	s_waitcnt lgkmcnt(0)
	s_cmp_eq_u32 s53, 16
	s_cbranch_scc1 .Lgm_skip1
	v_mfma_f32_16x16x32_bf16 v[118:121], v[218:221], v[182:185], v[118:121]
	v_mfma_f32_16x16x32_bf16 v[114:117], v[226:229], v[182:185], v[114:117]
	v_mfma_f32_16x16x32_bf16 v[102:105], v[218:221], v[190:193], v[102:105]
	v_mfma_f32_16x16x32_bf16 v[98:101], v[226:229], v[190:193], v[98:101]
	v_mfma_f32_16x16x32_bf16 v[86:89], v[218:221], v[198:201], v[86:89]
	v_mfma_f32_16x16x32_bf16 v[82:85], v[226:229], v[198:201], v[82:85]
	v_mfma_f32_16x16x32_bf16 v[70:73], v[218:221], v[210:213], v[70:73]
	v_mfma_f32_16x16x32_bf16 v[66:69], v[226:229], v[210:213], v[66:69]
	v_mfma_f32_16x16x32_bf16 v[118:121], v[222:225], v[186:189], v[118:121]
	v_mfma_f32_16x16x32_bf16 v[114:117], v[230:233], v[186:189], v[114:117]
	v_mfma_f32_16x16x32_bf16 v[102:105], v[222:225], v[194:197], v[102:105]
	v_mfma_f32_16x16x32_bf16 v[98:101], v[230:233], v[194:197], v[98:101]
	v_mfma_f32_16x16x32_bf16 v[86:89], v[222:225], v[206:209], v[86:89]
	v_mfma_f32_16x16x32_bf16 v[82:85], v[230:233], v[206:209], v[82:85]
	v_mfma_f32_16x16x32_bf16 v[70:73], v[222:225], v[214:217], v[70:73]
	v_mfma_f32_16x16x32_bf16 v[66:69], v[230:233], v[214:217], v[66:69]

.Lgm_skip2:
	s_setprio 0
	s_add_i32 s26, 0, 0x18000
	v_add_u32_e32 v178, s26, v175
	s_barrier
	ds_read_b128 v[130:133], v178
	ds_read_b128 v[134:137], v178 offset:1024
	ds_read_b128 v[156:159], v178 offset:2048
	ds_read_b128 v[178:181], v178 offset:3072
	s_add_u32 s24, s24, s62
	s_addc_u32 s25, s25, 0
	s_mov_b32 m0, s37
	v_lshl_add_u64 v[218:219], s[24:25], 0, v[146:147]
	ds_read_b128 v[182:185], v177 offset:32768
	ds_read_b128 v[186:189], v177 offset:33792
	ds_read_b128 v[190:193], v177 offset:34816
	ds_read_b128 v[194:197], v177 offset:35840
	ds_read_b128 v[198:201], v177 offset:36864
	ds_read_b128 v[206:209], v177 offset:37888
	ds_read_b128 v[210:213], v177 offset:38912
	ds_read_b128 v[214:217], v177 offset:39936
	global_load_lds_dwordx4 v[218:219], off
	v_lshl_add_u64 v[218:219], s[24:25], 0, v[148:149]
	s_mov_b32 m0, s38
	s_nop 0
	global_load_lds_dwordx4 v[218:219], off
	s_waitcnt lgkmcnt(8)
	s_barrier
	s_waitcnt lgkmcnt(0)
	s_setprio 1
	s_waitcnt lgkmcnt(0)
	v_mfma_f32_16x16x32_bf16 v[126:129], v[130:133], v[182:185], v[126:129]
	v_mfma_f32_16x16x32_bf16 v[122:125], v[156:159], v[182:185], v[122:125]
	v_mfma_f32_16x16x32_bf16 v[110:113], v[130:133], v[190:193], v[110:113]
	v_mfma_f32_16x16x32_bf16 v[106:109], v[156:159], v[190:193], v[106:109]
	v_mfma_f32_16x16x32_bf16 v[94:97], v[130:133], v[198:201], v[94:97]
	v_mfma_f32_16x16x32_bf16 v[90:93], v[156:159], v[198:201], v[90:93]
	v_mfma_f32_16x16x32_bf16 v[78:81], v[130:133], v[210:213], v[78:81]
	v_mfma_f32_16x16x32_bf16 v[74:77], v[156:159], v[210:213], v[74:77]
	v_mfma_f32_16x16x32_bf16 v[126:129], v[134:137], v[186:189], v[126:129]
	v_mfma_f32_16x16x32_bf16 v[122:125], v[178:181], v[186:189], v[122:125]
	v_mfma_f32_16x16x32_bf16 v[110:113], v[134:137], v[194:197], v[110:113]
	v_mfma_f32_16x16x32_bf16 v[106:109], v[178:181], v[194:197], v[106:109]
	v_mfma_f32_16x16x32_bf16 v[94:97], v[134:137], v[206:209], v[94:97]
	v_mfma_f32_16x16x32_bf16 v[90:93], v[178:181], v[206:209], v[90:93]
	v_mfma_f32_16x16x32_bf16 v[78:81], v[134:137], v[214:217], v[78:81]
	v_mfma_f32_16x16x32_bf16 v[74:77], v[178:181], v[214:217], v[74:77]
	s_setprio 0
	s_barrier
	s_add_i32 s24, 0, 0x1c000
	s_add_i32 s25, s26, s34
	v_add_u32_e32 v230, s24, v175
	v_lshl_add_u64 v[202:203], v[202:203], 0, s[88:89]
	s_mov_b32 m0, s25
	s_cmp_eq_u32 s53, 16
	s_cbranch_scc1 .Lgm_ry2
	ds_read_b128 v[218:221], v230
	ds_read_b128 v[222:225], v230 offset:1024
	ds_read_b128 v[226:229], v230 offset:2048
	ds_read_b128 v[230:233], v230 offset:3072
.Lgm_ry2:
	global_load_lds_dwordx4 v[202:203], off
	v_lshl_add_u64 v[202:203], v[234:235], 0, s[88:89]
	s_add_i32 m0, s25, 0x2000
	s_nop 0
	global_load_lds_dwordx4 v[202:203], off
	s_barrier
	s_waitcnt lgkmcnt(0)
	s_setprio 1
	s_waitcnt lgkmcnt(0)
	s_cmp_eq_u32 s53, 16
	s_cbranch_scc1 .Lgm_skip3
	v_mfma_f32_16x16x32_bf16 v[118:121], v[218:221], v[182:185], v[118:121]
	v_mfma_f32_16x16x32_bf16 v[114:117], v[226:229], v[182:185], v[114:117]
	v_mfma_f32_16x16x32_bf16 v[102:105], v[218:221], v[190:193], v[102:105]
	v_mfma_f32_16x16x32_bf16 v[98:101], v[226:229], v[190:193], v[98:101]
	v_mfma_f32_16x16x32_bf16 v[86:89], v[218:221], v[198:201], v[86:89]
	v_mfma_f32_16x16x32_bf16 v[82:85], v[226:229], v[198:201], v[82:85]
	v_mfma_f32_16x16x32_bf16 v[70:73], v[218:221], v[210:213], v[70:73]
	v_mfma_f32_16x16x32_bf16 v[66:69], v[226:229], v[210:213], v[66:69]
	v_mfma_f32_16x16x32_bf16 v[118:121], v[222:225], v[186:189], v[118:121]
	v_mfma_f32_16x16x32_bf16 v[114:117], v[230:233], v[186:189], v[114:117]
	v_mfma_f32_16x16x32_bf16 v[102:105], v[222:225], v[194:197], v[102:105]
	v_mfma_f32_16x16x32_bf16 v[98:101], v[230:233], v[194:197], v[98:101]
	v_mfma_f32_16x16x32_bf16 v[86:89], v[222:225], v[206:209], v[86:89]
	v_mfma_f32_16x16x32_bf16 v[82:85], v[230:233], v[206:209], v[82:85]
	v_mfma_f32_16x16x32_bf16 v[70:73], v[222:225], v[214:217], v[70:73]
	v_mfma_f32_16x16x32_bf16 v[66:69], v[230:233], v[214:217], v[66:69]
